# P7 modulate row loop: gain/scale/shift vectors of column blocks 1..3 loaded up front with the row (one exposed latency per row instead of four)
# speedup vs baseline: 1.0124x; 1.0124x over previous
; __device__ __forceinline__ unsigned pk2(float lo, float hi) { return cvt_pk_bf16(lo, hi); }
; template <int WHICH> __device__ __forceinline__ void phase_modulate(const Params& P, const Ctx& C) {
;     ...
;     for (int r = gw; r < NR; r += NGW) {
;         const float* xr = (WHICH == 0) ? (r < NPR ? P.in[0] + (size_t)r * DM : P.in[1] + (size_t)(r - NPR) * DM) : (const float*)(ws + WS_X1) + (size_t)r * DM;
;         const float* mr = MOD + (size_t)pg8::mod_row(r) * 6144 + (WHICH == 0 ? 0 : 3072);
;         f32x4 v[4]; float ss = 0.f;
; #pragma unroll
;         for (int j = 0; j < 4; ++j) { v[j] = *(const f32x4*)(xr + 4 * lane + 256 * j); ss += (v[j][0] * v[j][0] + v[j][1] * v[j][1]) + (v[j][2] * v[j][2] + v[j][3] * v[j][3]); }
;         const float rstd = 1.0f / sqrtf(wave_sum(ss) * (1.f / DM) + EPS);
; #pragma unroll
;         for (int j = 0; j < 4; ++j) { const int c = 4 * lane + 256 * j;
;             const f32x4 g = *(const f32x4*)(gn + c), sh = *(const f32x4*)(mr + c), sc = *(const f32x4*)(mr + 1024 + c);
;             const f32x4 o = v[j] * rstd * g * (sc + 1.0f) + sh;
;             u32x2 w; w.x = pk2(o[0], o[1]); w.y = pk2(o[2], o[3]);
;             *(u32x2*)(H + (size_t)r * DM + c) = w; }
;     }
.LBB0_1780:
	v_lshl_add_u64 v[20:21], s[6:7], 0, v[6:7]
	s_add_i32 s2, s8, 0xffffc000
	v_lshl_add_u64 v[22:23], s[6:7], 0, v[4:5]
	v_add_co_u32_e32 v36, vcc, s0, v20
	s_lshr_b32 s21, s2, 2
	v_add_co_u32_e64 v44, s[2:3], s11, v22
	v_addc_co_u32_e32 v37, vcc, 0, v21, vcc
	global_load_dwordx4 v[16:19], v[2:3], off
	v_addc_co_u32_e64 v45, s[2:3], 0, v23, s[2:3]
	global_load_dwordx4 v[20:23], v[36:37], off
	global_load_dwordx4 v[24:27], v[36:37], off offset:1024
	global_load_dwordx4 v[28:31], v[36:37], off offset:3072
	global_load_dwordx4 v[32:35], v[36:37], off offset:2048
	s_ashr_i32 s20, s8, 13
	s_add_i32 s21, s21, 2
	s_cmpk_lt_i32 s8, 0x4000
	s_cselect_b32 s2, s20, s21
	s_mul_hi_i32 s3, s2, 0x6000
	s_mulk_i32 s2, 0x6000
	s_add_u32 s2, s6, s2
	s_addc_u32 s3, s7, s3
	v_lshl_add_u64 v[36:37], v[0:1], 2, s[2:3]
	v_add_co_u32_e32 v48, vcc, s9, v36
	v_lshl_add_u64 v[46:47], v[36:37], 0, s[16:17]
	s_nop 0
	v_addc_co_u32_e32 v49, vcc, 0, v37, vcc
	v_lshl_add_u64 v[50:51], v[36:37], 0, s[18:19]
	global_load_dwordx4 v[36:39], v[48:49], off
	global_load_dwordx4 v[40:43], v[48:49], off offset:-4096
	global_load_dwordx4 v[68:71], v[2:3], off offset:1024
	global_load_dwordx4 v[72:75], v[50:51], off offset:1024
	global_load_dwordx4 v[76:79], v[46:47], off offset:1024
	global_load_dwordx4 v[80:83], v[2:3], off offset:2048
	global_load_dwordx4 v[84:87], v[50:51], off offset:2048
	global_load_dwordx4 v[88:91], v[46:47], off offset:2048
	global_load_dwordx4 v[92:95], v[2:3], off offset:3072
	global_load_dwordx4 v[96:99], v[50:51], off offset:3072
	global_load_dwordx4 v[100:103], v[46:47], off offset:3072
	s_add_i32 s8, s8, s10
	v_lshl_add_u64 v[4:5], v[4:5], 0, s[12:13]
	v_lshl_add_u64 v[6:7], v[6:7], 0, s[14:15]
	s_cmpk_lt_i32 s8, 0x4200
	s_waitcnt vmcnt(0)
	v_pk_mul_f32 v[48:49], v[22:23], v[22:23]
	v_pk_mul_f32 v[52:53], v[20:21], v[20:21]
	v_pk_mul_f32 v[54:55], v[26:27], v[26:27]
	v_pk_mul_f32 v[56:57], v[24:25], v[24:25]
	v_pk_mov_b32 v[62:63], v[52:53], v[48:49] op_sel:[1,0]
	v_mov_b32_e32 v53, v49
	v_pk_mov_b32 v[48:49], v[56:57], v[54:55] op_sel:[1,0]
	v_mov_b32_e32 v57, v55
	v_mul_f32_e32 v61, v28, v28
	v_mul_f32_e32 v58, v33, v33
	v_mul_f32_e32 v60, v35, v35
	v_pk_add_f32 v[52:53], v[62:63], v[52:53]
	v_pk_add_f32 v[48:49], v[48:49], v[56:57]
	v_mul_f32_e32 v64, v29, v29
	v_mul_f32_e32 v65, v30, v30
	v_mul_f32_e32 v66, v31, v31
	v_pk_fma_f32 v[54:55], v[32:33], v[32:33], v[58:59] op_sel_hi:[1,1,0]
	v_pk_fma_f32 v[58:59], v[34:35], v[34:35], v[60:61] op_sel_hi:[1,1,0]
	v_pk_add_f32 v[52:53], v[52:53], v[52:53] op_sel:[0,1] op_sel_hi:[1,0]
	v_pk_add_f32 v[48:49], v[48:49], v[48:49] op_sel:[0,1] op_sel_hi:[1,0]
	v_mov_b32_e32 v55, v65
	v_mov_b32_e32 v59, v66
	v_mov_b32_e32 v53, v61
	v_mov_b32_e32 v49, v64
	v_pk_add_f32 v[54:55], v[54:55], v[58:59]
	v_pk_add_f32 v[48:49], v[52:53], v[48:49]
	v_pk_add_f32 v[36:37], v[36:37], 1.0 op_sel_hi:[1,0]
	v_pk_add_f32 v[48:49], v[48:49], v[54:55]
	v_pk_add_f32 v[38:39], v[38:39], 1.0 op_sel_hi:[1,0]
	v_add_f32_e32 v48, v48, v49
	ds_bpermute_b32 v49, v8, v48
	s_waitcnt lgkmcnt(0)
	v_add_f32_e32 v48, v48, v49
	ds_bpermute_b32 v49, v9, v48
	s_waitcnt lgkmcnt(0)
	v_add_f32_e32 v48, v48, v49
	ds_bpermute_b32 v49, v10, v48
	s_waitcnt lgkmcnt(0)
	v_add_f32_e32 v48, v48, v49
	ds_bpermute_b32 v49, v11, v48
	s_waitcnt lgkmcnt(0)
	v_add_f32_e32 v48, v48, v49
	ds_bpermute_b32 v49, v12, v48
	s_waitcnt lgkmcnt(0)
	v_add_f32_e32 v48, v48, v49
	ds_bpermute_b32 v49, v13, v48
	s_waitcnt lgkmcnt(0)
	v_add_f32_e32 v48, v48, v49
	v_fmamk_f32 v48, v48, 0x3a800000, v14
	v_mul_f32_e32 v49, 0x4f800000, v48
	v_cmp_gt_f32_e32 vcc, s1, v48
	s_nop 1
	v_cndmask_b32_e32 v48, v48, v49, vcc
	v_sqrt_f32_e32 v49, v48
	s_nop 0
	v_add_u32_e32 v52, -1, v49
	v_add_u32_e32 v53, 1, v49
	v_fma_f32 v54, -v52, v49, v48
	v_fma_f32 v55, -v53, v49, v48
	v_cmp_ge_f32_e64 s[2:3], 0, v54
	s_nop 1
	v_cndmask_b32_e64 v49, v49, v52, s[2:3]
	v_cmp_lt_f32_e64 s[2:3], 0, v55
	s_nop 1
	v_cndmask_b32_e64 v49, v49, v53, s[2:3]
	v_mul_f32_e32 v52, 0x37800000, v49
	v_cndmask_b32_e32 v49, v49, v52, vcc
	v_cmp_class_f32_e32 vcc, v48, v15
	s_nop 1
	v_cndmask_b32_e32 v48, v49, v48, vcc
	v_div_scale_f32 v49, s[2:3], v48, v48, 1.0
	v_rcp_f32_e32 v53, v49
	v_div_scale_f32 v52, vcc, 1.0, v48, 1.0
	v_fma_f32 v54, -v49, v53, 1.0
	v_fmac_f32_e32 v53, v54, v53
	v_mul_f32_e32 v54, v52, v53
	v_fma_f32 v55, -v49, v54, v52
	v_fmac_f32_e32 v54, v55, v53
	v_fma_f32 v49, -v49, v54, v52
	v_div_fmas_f32 v49, v49, v53, v54
	v_div_fixup_f32 v48, v49, v48, 1.0
	v_pk_mul_f32 v[20:21], v[20:21], v[48:49] op_sel_hi:[1,0]
	v_pk_mul_f32 v[22:23], v[22:23], v[48:49] op_sel_hi:[1,0]
	v_pk_mul_f32 v[16:17], v[16:17], v[20:21]
	v_pk_mul_f32 v[18:19], v[18:19], v[22:23]
	v_pk_fma_f32 v[16:17], v[36:37], v[16:17], v[40:41]
	v_pk_fma_f32 v[18:19], v[38:39], v[18:19], v[42:43]
	v_cvt_pk_bf16_f32 v16, v16, v17
	v_pk_mul_f32 v[24:25], v[24:25], v[48:49] op_sel_hi:[1,0]
	v_cvt_pk_bf16_f32 v17, v18, v19
	global_store_dwordx2 v[44:45], v[16:17], off
	s_nop 0
	v_pk_mul_f32 v[26:27], v[26:27], v[48:49] op_sel_hi:[1,0]
	v_pk_mul_f32 v[32:33], v[32:33], v[48:49] op_sel_hi:[1,0]
	v_pk_mul_f32 v[34:35], v[34:35], v[48:49] op_sel_hi:[1,0]
	v_pk_mul_f32 v[28:29], v[28:29], v[48:49] op_sel_hi:[1,0]
	v_pk_mul_f32 v[30:31], v[30:31], v[48:49] op_sel_hi:[1,0]
	v_pk_mul_f32 v[16:17], v[68:69], v[24:25]
	v_pk_add_f32 v[20:21], v[72:73], 1.0 op_sel_hi:[1,0]
	v_pk_mul_f32 v[18:19], v[70:71], v[26:27]
	v_pk_add_f32 v[22:23], v[74:75], 1.0 op_sel_hi:[1,0]
	v_pk_fma_f32 v[16:17], v[20:21], v[16:17], v[76:77]
	v_pk_fma_f32 v[18:19], v[22:23], v[18:19], v[78:79]
	v_cvt_pk_bf16_f32 v16, v16, v17
	s_nop 0
	v_cvt_pk_bf16_f32 v17, v18, v19
	global_store_dwordx2 v[44:45], v[16:17], off offset:512
	s_nop 0
	v_pk_mul_f32 v[16:17], v[32:33], v[80:81]
	v_pk_add_f32 v[20:21], v[84:85], 1.0 op_sel_hi:[1,0]
	v_pk_mul_f32 v[18:19], v[34:35], v[82:83]
	v_pk_add_f32 v[22:23], v[86:87], 1.0 op_sel_hi:[1,0]
	v_pk_fma_f32 v[16:17], v[16:17], v[20:21], v[88:89]
	v_pk_fma_f32 v[18:19], v[18:19], v[22:23], v[90:91]
	v_cvt_pk_bf16_f32 v16, v16, v17
	s_nop 0
	v_cvt_pk_bf16_f32 v17, v18, v19
	global_store_dwordx2 v[44:45], v[16:17], off offset:1024
	s_nop 0
	v_pk_mul_f32 v[16:17], v[28:29], v[92:93]
	v_pk_add_f32 v[20:21], v[96:97], 1.0 op_sel_hi:[1,0]
	v_pk_mul_f32 v[18:19], v[30:31], v[94:95]
	v_pk_add_f32 v[22:23], v[98:99], 1.0 op_sel_hi:[1,0]
	v_pk_fma_f32 v[16:17], v[16:17], v[20:21], v[100:101]
	v_pk_fma_f32 v[18:19], v[18:19], v[22:23], v[102:103]
	v_cvt_pk_bf16_f32 v16, v16, v17
	s_nop 0
	v_cvt_pk_bf16_f32 v17, v18, v19
	global_store_dwordx2 v[44:45], v[16:17], off offset:1536
	s_cbranch_scc1 .LBB0_1780
